# attention phase: the workgroups of XCDs 4-7 (stick-breaking sample class, ~25 us of slack) start ~20 us late (on E1+E3+E25)
# speedup vs baseline: 1.0035x; 1.0004x over previous
.LBB0_609:
	s_or_b64 exec, exec, s[0:1]
	s_mov_b64 s[0:1], 0
	v_mov_b32_e32 v1, v0
	v_readlane_b32 s72, v252, 0
	v_readlane_b32 s2, v252, 3
	s_waitcnt lgkmcnt(0)
	s_barrier
	s_bitcmp0_b32 s72, 2
	s_cbranch_scc1 .Latt_nd
	s_movk_i32 s3, 5
.Latt_dl:
	s_sleep 127
	s_add_i32 s3, s3, -1
	s_cmp_lg_u32 s3, 0
	s_cbranch_scc1 .Latt_dl
.Latt_nd:
	s_and_b32 s3, s2, 7
	s_cmp_lg_u32 s3, 0
	s_cbranch_scc1 .LBB0_611
	s_ashr_i32 s3, s72, 31
	s_lshr_b32 s3, s3, 29
	s_add_i32 s3, s72, s3
	s_ashr_i32 s4, s3, 3
	s_and_b32 s3, s3, -8
	s_ashr_i32 s2, s2, 3
	s_sub_i32 s3, s72, s3
	s_mul_i32 s2, s3, s2
	s_add_i32 s72, s2, s4
